# NSA top-k radix search: early exit as soon as exactly 13 candidates are above the threshold; on top of v54
# baseline (speedup 1.0000x reference)
; __device__ __forceinline__ float rdlane(float v, int l) { return __int_as_float(__builtin_amdgcn_readlane(__float_as_int(v), l)); }
; __device__ __forceinline__ void nsa_unit(Frame& F, int b, int g, int c) {
;     ...
;             if (c >= 16) {
;                 const bool cand = (lane >= 1) && (lane <= c - 2);
;                 const float v = cand ? impG[tl * 64 + lane] + impL[tl * 64 + lane] : -__builtin_inff();
;                 int rank = 0;
;                 for (int i = 0; i < 64; ++i) { const float vi = rdlane(v, i); rank += ((vi > v) || (vi == v && i < lane)) ? 1 : 0; }
;                 mk = __ballot(cand && rank < 13) | 1ull | (1ull << c) | (1ull << (c - 1));
.LBB0_869:
	s_or_b64 exec, exec, s[0:1]
	v_ashrrev_i32_e32 v3, 31, v2
	v_or_b32_e32 v3, 0x80000000, v3
	v_xor_b32_e32 v3, v2, v3
	s_mov_b32 s98, 0
	s_or_b32 s100, s98, 0x80000000
	v_cmp_le_u32_e32 vcc, s100, v3
	s_and_b64 s[0:1], vcc, s[8:9]
	s_bcnt1_i32_b64 s101, s[0:1]
	s_cmp_eq_u32 s101, 13
	s_cbranch_scc1 .Lrk_exact_870
	s_cmp_ge_u32 s101, 13
	s_cselect_b32 s98, s100, s98
	s_or_b32 s100, s98, 0x40000000
	v_cmp_le_u32_e32 vcc, s100, v3
	s_and_b64 s[0:1], vcc, s[8:9]
	s_bcnt1_i32_b64 s101, s[0:1]
	s_cmp_eq_u32 s101, 13
	s_cbranch_scc1 .Lrk_exact_870
	s_cmp_ge_u32 s101, 13
	s_cselect_b32 s98, s100, s98
	s_or_b32 s100, s98, 0x20000000
	v_cmp_le_u32_e32 vcc, s100, v3
	s_and_b64 s[0:1], vcc, s[8:9]
	s_bcnt1_i32_b64 s101, s[0:1]
	s_cmp_eq_u32 s101, 13
	s_cbranch_scc1 .Lrk_exact_870
	s_cmp_ge_u32 s101, 13
	s_cselect_b32 s98, s100, s98
	s_or_b32 s100, s98, 0x10000000
	v_cmp_le_u32_e32 vcc, s100, v3
	s_and_b64 s[0:1], vcc, s[8:9]
	s_bcnt1_i32_b64 s101, s[0:1]
	s_cmp_eq_u32 s101, 13
	s_cbranch_scc1 .Lrk_exact_870
	s_cmp_ge_u32 s101, 13
	s_cselect_b32 s98, s100, s98
	s_or_b32 s100, s98, 0x8000000
	v_cmp_le_u32_e32 vcc, s100, v3
	s_and_b64 s[0:1], vcc, s[8:9]
	s_bcnt1_i32_b64 s101, s[0:1]
	s_cmp_eq_u32 s101, 13
	s_cbranch_scc1 .Lrk_exact_870
	s_cmp_ge_u32 s101, 13
	s_cselect_b32 s98, s100, s98
	s_or_b32 s100, s98, 0x4000000
	v_cmp_le_u32_e32 vcc, s100, v3
	s_and_b64 s[0:1], vcc, s[8:9]
	s_bcnt1_i32_b64 s101, s[0:1]
	s_cmp_eq_u32 s101, 13
	s_cbranch_scc1 .Lrk_exact_870
	s_cmp_ge_u32 s101, 13
	s_cselect_b32 s98, s100, s98
	s_or_b32 s100, s98, 0x2000000
	v_cmp_le_u32_e32 vcc, s100, v3
	s_and_b64 s[0:1], vcc, s[8:9]
	s_bcnt1_i32_b64 s101, s[0:1]
	s_cmp_eq_u32 s101, 13
	s_cbranch_scc1 .Lrk_exact_870
	s_cmp_ge_u32 s101, 13
	s_cselect_b32 s98, s100, s98
	s_or_b32 s100, s98, 0x1000000
	v_cmp_le_u32_e32 vcc, s100, v3
	s_and_b64 s[0:1], vcc, s[8:9]
	s_bcnt1_i32_b64 s101, s[0:1]
	s_cmp_eq_u32 s101, 13
	s_cbranch_scc1 .Lrk_exact_870
	s_cmp_ge_u32 s101, 13
	s_cselect_b32 s98, s100, s98
	s_or_b32 s100, s98, 0x800000
	v_cmp_le_u32_e32 vcc, s100, v3
	s_and_b64 s[0:1], vcc, s[8:9]
	s_bcnt1_i32_b64 s101, s[0:1]
	s_cmp_eq_u32 s101, 13
	s_cbranch_scc1 .Lrk_exact_870
	s_cmp_ge_u32 s101, 13
	s_cselect_b32 s98, s100, s98
	s_or_b32 s100, s98, 0x400000
	v_cmp_le_u32_e32 vcc, s100, v3
	s_and_b64 s[0:1], vcc, s[8:9]
	s_bcnt1_i32_b64 s101, s[0:1]
	s_cmp_eq_u32 s101, 13
	s_cbranch_scc1 .Lrk_exact_870
	s_cmp_ge_u32 s101, 13
	s_cselect_b32 s98, s100, s98
	s_or_b32 s100, s98, 0x200000
	v_cmp_le_u32_e32 vcc, s100, v3
	s_and_b64 s[0:1], vcc, s[8:9]
	s_bcnt1_i32_b64 s101, s[0:1]
	s_cmp_eq_u32 s101, 13
	s_cbranch_scc1 .Lrk_exact_870
	s_cmp_ge_u32 s101, 13
	s_cselect_b32 s98, s100, s98
	s_or_b32 s100, s98, 0x100000
	v_cmp_le_u32_e32 vcc, s100, v3
	s_and_b64 s[0:1], vcc, s[8:9]
	s_bcnt1_i32_b64 s101, s[0:1]
	s_cmp_eq_u32 s101, 13
	s_cbranch_scc1 .Lrk_exact_870
	s_cmp_ge_u32 s101, 13
	s_cselect_b32 s98, s100, s98
	s_or_b32 s100, s98, 0x80000
	v_cmp_le_u32_e32 vcc, s100, v3
	s_and_b64 s[0:1], vcc, s[8:9]
	s_bcnt1_i32_b64 s101, s[0:1]
	s_cmp_eq_u32 s101, 13
	s_cbranch_scc1 .Lrk_exact_870
	s_cmp_ge_u32 s101, 13
	s_cselect_b32 s98, s100, s98
	s_or_b32 s100, s98, 0x40000
	v_cmp_le_u32_e32 vcc, s100, v3
	s_and_b64 s[0:1], vcc, s[8:9]
	s_bcnt1_i32_b64 s101, s[0:1]
	s_cmp_eq_u32 s101, 13
	s_cbranch_scc1 .Lrk_exact_870
	s_cmp_ge_u32 s101, 13
	s_cselect_b32 s98, s100, s98
	s_or_b32 s100, s98, 0x20000
	v_cmp_le_u32_e32 vcc, s100, v3
	s_and_b64 s[0:1], vcc, s[8:9]
	s_bcnt1_i32_b64 s101, s[0:1]
	s_cmp_eq_u32 s101, 13
	s_cbranch_scc1 .Lrk_exact_870
	s_cmp_ge_u32 s101, 13
	s_cselect_b32 s98, s100, s98
	s_or_b32 s100, s98, 0x10000
	v_cmp_le_u32_e32 vcc, s100, v3
	s_and_b64 s[0:1], vcc, s[8:9]
	s_bcnt1_i32_b64 s101, s[0:1]
	s_cmp_eq_u32 s101, 13
	s_cbranch_scc1 .Lrk_exact_870
	s_cmp_ge_u32 s101, 13
	s_cselect_b32 s98, s100, s98
	s_or_b32 s100, s98, 0x8000
	v_cmp_le_u32_e32 vcc, s100, v3
	s_and_b64 s[0:1], vcc, s[8:9]
	s_bcnt1_i32_b64 s101, s[0:1]
	s_cmp_eq_u32 s101, 13
	s_cbranch_scc1 .Lrk_exact_870
; __device__ __forceinline__ float rdlane(float v, int l) { return __int_as_float(__builtin_amdgcn_readlane(__float_as_int(v), l)); }
; __device__ __forceinline__ void nsa_unit(Frame& F, int b, int g, int c) {
;     ...
;             if (c >= 16) {
;                 const bool cand = (lane >= 1) && (lane <= c - 2);
;                 const float v = cand ? impG[tl * 64 + lane] + impL[tl * 64 + lane] : -__builtin_inff();
;                 int rank = 0;
;                 for (int i = 0; i < 64; ++i) { const float vi = rdlane(v, i); rank += ((vi > v) || (vi == v && i < lane)) ? 1 : 0; }
;                 mk = __ballot(cand && rank < 13) | 1ull | (1ull << c) | (1ull << (c - 1));
;             } else mk = (2ull << c) - 1ull;
;             if (lane == 0) selm[tl] = mk;
;             wuni |= mk;
	s_cmp_ge_u32 s101, 13
	s_cselect_b32 s98, s100, s98
	s_or_b32 s100, s98, 0x4000
	v_cmp_le_u32_e32 vcc, s100, v3
	s_and_b64 s[0:1], vcc, s[8:9]
	s_bcnt1_i32_b64 s101, s[0:1]
	s_cmp_eq_u32 s101, 13
	s_cbranch_scc1 .Lrk_exact_870
	s_cmp_ge_u32 s101, 13
	s_cselect_b32 s98, s100, s98
	s_or_b32 s100, s98, 0x2000
	v_cmp_le_u32_e32 vcc, s100, v3
	s_and_b64 s[0:1], vcc, s[8:9]
	s_bcnt1_i32_b64 s101, s[0:1]
	s_cmp_eq_u32 s101, 13
	s_cbranch_scc1 .Lrk_exact_870
	s_cmp_ge_u32 s101, 13
	s_cselect_b32 s98, s100, s98
	s_or_b32 s100, s98, 0x1000
	v_cmp_le_u32_e32 vcc, s100, v3
	s_and_b64 s[0:1], vcc, s[8:9]
	s_bcnt1_i32_b64 s101, s[0:1]
	s_cmp_eq_u32 s101, 13
	s_cbranch_scc1 .Lrk_exact_870
	s_cmp_ge_u32 s101, 13
	s_cselect_b32 s98, s100, s98
	s_or_b32 s100, s98, 0x800
	v_cmp_le_u32_e32 vcc, s100, v3
	s_and_b64 s[0:1], vcc, s[8:9]
	s_bcnt1_i32_b64 s101, s[0:1]
	s_cmp_eq_u32 s101, 13
	s_cbranch_scc1 .Lrk_exact_870
	s_cmp_ge_u32 s101, 13
	s_cselect_b32 s98, s100, s98
	s_or_b32 s100, s98, 0x400
	v_cmp_le_u32_e32 vcc, s100, v3
	s_and_b64 s[0:1], vcc, s[8:9]
	s_bcnt1_i32_b64 s101, s[0:1]
	s_cmp_eq_u32 s101, 13
	s_cbranch_scc1 .Lrk_exact_870
	s_cmp_ge_u32 s101, 13
	s_cselect_b32 s98, s100, s98
	s_or_b32 s100, s98, 0x200
	v_cmp_le_u32_e32 vcc, s100, v3
	s_and_b64 s[0:1], vcc, s[8:9]
	s_bcnt1_i32_b64 s101, s[0:1]
	s_cmp_eq_u32 s101, 13
	s_cbranch_scc1 .Lrk_exact_870
	s_cmp_ge_u32 s101, 13
	s_cselect_b32 s98, s100, s98
	s_or_b32 s100, s98, 0x100
	v_cmp_le_u32_e32 vcc, s100, v3
	s_and_b64 s[0:1], vcc, s[8:9]
	s_bcnt1_i32_b64 s101, s[0:1]
	s_cmp_eq_u32 s101, 13
	s_cbranch_scc1 .Lrk_exact_870
	s_cmp_ge_u32 s101, 13
	s_cselect_b32 s98, s100, s98
	s_or_b32 s100, s98, 0x80
	v_cmp_le_u32_e32 vcc, s100, v3
	s_and_b64 s[0:1], vcc, s[8:9]
	s_bcnt1_i32_b64 s101, s[0:1]
	s_cmp_eq_u32 s101, 13
	s_cbranch_scc1 .Lrk_exact_870
	s_cmp_ge_u32 s101, 13
	s_cselect_b32 s98, s100, s98
	s_or_b32 s100, s98, 64
	v_cmp_le_u32_e32 vcc, s100, v3
	s_and_b64 s[0:1], vcc, s[8:9]
	s_bcnt1_i32_b64 s101, s[0:1]
	s_cmp_eq_u32 s101, 13
	s_cbranch_scc1 .Lrk_exact_870
	s_cmp_ge_u32 s101, 13
	s_cselect_b32 s98, s100, s98
	s_or_b32 s100, s98, 32
	v_cmp_le_u32_e32 vcc, s100, v3
	s_and_b64 s[0:1], vcc, s[8:9]
	s_bcnt1_i32_b64 s101, s[0:1]
	s_cmp_eq_u32 s101, 13
	s_cbranch_scc1 .Lrk_exact_870
	s_cmp_ge_u32 s101, 13
	s_cselect_b32 s98, s100, s98
	s_or_b32 s100, s98, 16
	v_cmp_le_u32_e32 vcc, s100, v3
	s_and_b64 s[0:1], vcc, s[8:9]
	s_bcnt1_i32_b64 s101, s[0:1]
	s_cmp_eq_u32 s101, 13
	s_cbranch_scc1 .Lrk_exact_870
	s_cmp_ge_u32 s101, 13
	s_cselect_b32 s98, s100, s98
	s_or_b32 s100, s98, 8
	v_cmp_le_u32_e32 vcc, s100, v3
	s_and_b64 s[0:1], vcc, s[8:9]
	s_bcnt1_i32_b64 s101, s[0:1]
	s_cmp_eq_u32 s101, 13
	s_cbranch_scc1 .Lrk_exact_870
	s_cmp_ge_u32 s101, 13
	s_cselect_b32 s98, s100, s98
	s_or_b32 s100, s98, 4
	v_cmp_le_u32_e32 vcc, s100, v3
	s_and_b64 s[0:1], vcc, s[8:9]
	s_bcnt1_i32_b64 s101, s[0:1]
	s_cmp_eq_u32 s101, 13
	s_cbranch_scc1 .Lrk_exact_870
	s_cmp_ge_u32 s101, 13
	s_cselect_b32 s98, s100, s98
	s_or_b32 s100, s98, 2
	v_cmp_le_u32_e32 vcc, s100, v3
	s_and_b64 s[0:1], vcc, s[8:9]
	s_bcnt1_i32_b64 s101, s[0:1]
	s_cmp_eq_u32 s101, 13
	s_cbranch_scc1 .Lrk_exact_870
	s_cmp_ge_u32 s101, 13
	s_cselect_b32 s98, s100, s98
	s_or_b32 s100, s98, 1
	v_cmp_le_u32_e32 vcc, s100, v3
	s_and_b64 s[0:1], vcc, s[8:9]
	s_bcnt1_i32_b64 s101, s[0:1]
	s_cmp_eq_u32 s101, 13
	s_cbranch_scc1 .Lrk_exact_870
	s_cmp_ge_u32 s101, 13
	s_cselect_b32 s98, s100, s98
	v_cmp_lt_u32_e32 vcc, s98, v3
	s_and_b64 s[0:1], vcc, s[8:9]
	s_bcnt1_i32_b64 s101, s[0:1]
	s_sub_i32 s99, 13, s101
	v_cmp_eq_u32_e32 vcc, s98, v3
	s_and_b64 vcc, vcc, s[8:9]
	s_nop 1
	v_mbcnt_lo_u32_b32 v4, vcc_lo, 0
	v_mbcnt_hi_u32_b32 v4, vcc_hi, v4
	v_cmp_gt_u32_e64 s[100:101], s99, v4
	s_and_b64 vcc, vcc, s[100:101]
	s_or_b64 vcc, vcc, s[0:1]
	s_branch .Lrk_done_870
.Lrk_exact_870:
	s_mov_b64 vcc, s[0:1]
.Lrk_done_870:
	s_or_b64 s[14:15], s[10:11], vcc
	s_or_b32 s14, s14, 1

; __device__ __forceinline__ void nsa_unit(Frame& F, int b, int g, int c) {
;     ...
;                 mk = __ballot(cand && rank < 13) | 1ull | (1ull << c) | (1ull << (c - 1));
;             } else mk = (2ull << c) - 1ull;
;             if (lane == 0) selm[tl] = mk;
;             wuni |= mk;
.Lrk_done_878:
	s_or_b64 s[16:17], s[10:11], vcc
	s_or_b32 s16, s16, 1

; __device__ __forceinline__ void nsa_unit(Frame& F, int b, int g, int c) {
;     ...
;                 mk = __ballot(cand && rank < 13) | 1ull | (1ull << c) | (1ull << (c - 1));
;             } else mk = (2ull << c) - 1ull;
;             if (lane == 0) selm[tl] = mk;
;             wuni |= mk;
.Lrk_done_886:
	s_or_b64 s[18:19], s[10:11], vcc
	s_or_b32 s18, s18, 1

; __device__ __forceinline__ void nsa_unit(Frame& F, int b, int g, int c) {
;     ...
;                 mk = __ballot(cand && rank < 13) | 1ull | (1ull << c) | (1ull << (c - 1));
;             } else mk = (2ull << c) - 1ull;
;             if (lane == 0) selm[tl] = mk;
;             wuni |= mk;
.Lrk_done_894:
	s_or_b64 s[20:21], s[10:11], vcc
	s_or_b32 s20, s20, 1

; __device__ __forceinline__ void nsa_unit(Frame& F, int b, int g, int c) {
;     ...
;                 mk = __ballot(cand && rank < 13) | 1ull | (1ull << c) | (1ull << (c - 1));
;             } else mk = (2ull << c) - 1ull;
;             if (lane == 0) selm[tl] = mk;
;             wuni |= mk;
.Lrk_done_902:
	s_or_b64 s[22:23], s[10:11], vcc
	s_or_b32 s22, s22, 1

; __device__ __forceinline__ void nsa_unit(Frame& F, int b, int g, int c) {
;     ...
;                 mk = __ballot(cand && rank < 13) | 1ull | (1ull << c) | (1ull << (c - 1));
;             } else mk = (2ull << c) - 1ull;
;             if (lane == 0) selm[tl] = mk;
;             wuni |= mk;
.Lrk_done_910:
	s_or_b64 s[24:25], s[10:11], vcc
	s_or_b32 s24, s24, 1

; __device__ __forceinline__ void nsa_unit(Frame& F, int b, int g, int c) {
;     ...
;                 mk = __ballot(cand && rank < 13) | 1ull | (1ull << c) | (1ull << (c - 1));
;             } else mk = (2ull << c) - 1ull;
;             if (lane == 0) selm[tl] = mk;
;             wuni |= mk;
.Lrk_done_948:
	s_or_b64 s[6:7], s[10:11], vcc
	s_or_b32 s6, s6, 1
	s_and_saveexec_b64 s[0:1], s[2:3]
	s_cbranch_execz .LBB0_916

; __device__ __forceinline__ void nsa_unit(Frame& F, int b, int g, int c) {
;     ...
;                 mk = __ballot(cand && rank < 13) | 1ull | (1ull << c) | (1ull << (c - 1));
;             } else mk = (2ull << c) - 1ull;
;             if (lane == 0) selm[tl] = mk;
;             wuni |= mk;
.Lrk_done_954:
	s_or_b64 s[12:13], s[10:11], vcc
	s_or_b32 s12, s12, 1
	s_and_saveexec_b64 s[0:1], s[2:3]
	s_cbranch_execnz .LBB0_918
	s_branch .LBB0_919
